# A-unit Q loads hoisted above K/V wait; barrier census loads parallelized; P3 KFT search as 6-step binary search
# speedup vs baseline: 1.0122x; 1.0058x over previous
.LBB0_180:
	v_readlane_b32 s6, v252, 57
	v_readlane_b32 s7, v252, 58
	v_readlane_b32 s8, v254, 24
	s_waitcnt lgkmcnt(0)
	s_mov_b64 s[10:11], exec
	s_mov_b64 exec, 0xffff
	v_mbcnt_lo_u32_b32 v18, -1, 0
	v_lshlrev_b32_e32 v18, 8, v18
	s_nop 1
	global_load_dword v19, v18, s[6:7] sc1
	s_waitcnt vmcnt(0)
	s_mov_b64 exec, s[10:11]
	s_nop 0
	v_readlane_b32 s6, v19, 0
	v_readlane_b32 s7, v19, 1
	v_readlane_b32 s9, v19, 2
	v_readlane_b32 s10, v19, 3
	v_mov_b32_e32 v0, s6
	v_mov_b32_e32 v2, s7
	v_mov_b32_e32 v3, s9
	v_mov_b32_e32 v4, s10
	v_readlane_b32 s6, v19, 4
	v_readlane_b32 s7, v19, 5
	v_readlane_b32 s9, v19, 6
	v_readlane_b32 s10, v19, 7
	v_mov_b32_e32 v5, s6
	v_mov_b32_e32 v6, s7
	v_mov_b32_e32 v7, s9
	v_mov_b32_e32 v8, s10
	v_readlane_b32 s6, v19, 8
	v_readlane_b32 s7, v19, 9
	v_readlane_b32 s9, v19, 10
	v_readlane_b32 s10, v19, 11
	v_mov_b32_e32 v9, s6
	v_mov_b32_e32 v10, s7
	v_mov_b32_e32 v11, s9
	v_mov_b32_e32 v12, s10
	v_readlane_b32 s6, v19, 12
	v_readlane_b32 s7, v19, 13
	v_readlane_b32 s9, v19, 14
	v_readlane_b32 s10, v19, 15
	v_mov_b32_e32 v13, s6
	v_mov_b32_e32 v14, s7
	v_mov_b32_e32 v15, s9
	v_mov_b32_e32 v16, s10
	v_add3_u32 v17, v0, v2, v3
	v_add3_u32 v17, v17, v4, v5
	v_add3_u32 v17, v17, v6, v7
	v_add3_u32 v17, v17, v8, v9
	v_add3_u32 v17, v17, v10, v11
	v_add3_u32 v17, v17, v12, v13
	v_add3_u32 v17, v17, v14, v15
	v_add_u32_e32 v17, v17, v16
	s_mov_b64 s[6:7], -1
	v_cmp_eq_u32_e32 vcc, s8, v17
	s_mov_b64 s[8:9], -1
	s_cbranch_vccnz .LBB0_179
	s_and_b32 s6, s24, 0xff
	s_cmp_eq_u32 s6, 0
	s_mov_b64 s[6:7], -1
	s_mov_b64 s[10:11], -1
	s_sleep 1
	s_cbranch_scc0 .LBB0_184
	v_readlane_b32 s6, v252, 55
	v_readlane_b32 s7, v252, 56
	s_nop 4
	global_load_dword v17, v1, s[6:7] sc1
	s_waitcnt vmcnt(0)
	v_cmp_eq_u32_e32 vcc, 0, v17
	s_cbranch_vccnz .LBB0_186
	s_mov_b64 s[10:11], 0
	s_mov_b64 s[6:7], -1

.LBB0_313:
	s_movk_i32 s4, 0x100
	v_cmp_gt_i32_e32 vcc, s4, v178
	v_lshlrev_b32_e32 v3, 1, v178
	s_waitcnt lgkmcnt(0)
	s_barrier
	s_and_saveexec_b64 s[4:5], vcc
	s_cbranch_execz .LBB0_322
	v_and_b32_e32 v4, 62, v3
	v_mov_b32_e32 v6, 0
	v_cmp_ne_u32_e32 vcc, 0, v4
	s_and_saveexec_b64 s[6:7], vcc
	s_cbranch_execz .LBB0_320
	v_readlane_b32 s8, v254, 42
	v_lshlrev_b32_e32 v8, 3, v178
	v_mov_b32_e32 v7, 0x41d00000
	v_mov_b32_e32 v5, s8
	ds_read_b32 v6, v5
	v_lshl_add_u32 v5, v3, 2, 0
	v_add_u32_e32 v5, 0x20400, v5
	ds_read_b32 v5, v5
	v_readlane_b32 s8, v254, 43
	s_waitcnt lgkmcnt(1)
	v_add_f32_e32 v6, v6, v6
	v_fmamk_f32 v7, v6, 0x3f317218, v7
	v_and_b32_e32 v6, 0xffffff00, v8
	v_add_u32_e32 v8, s8, v6
	v_mov_b32_e32 v9, 0
	v_mov_b32_e32 v10, v4
	v_add_u32_e32 v11, v9, v10
	v_lshrrev_b32_e32 v11, 1, v11
	v_lshl_add_u32 v12, v11, 2, v8
	ds_read_b32 v12, v12
	v_cmp_lt_u32_e32 vcc, v9, v10
	v_add_u32_e32 v13, 1, v11
	s_waitcnt lgkmcnt(0)
	v_sub_f32_e32 v12, v5, v12
	v_cmp_lt_f32_e64 s[40:41], v12, -v7
	s_nop 1
	s_and_b64 s[24:25], vcc, s[40:41]
	s_andn2_b64 s[40:41], vcc, s[40:41]
	s_nop 0
	v_cndmask_b32_e64 v9, v9, v13, s[24:25]
	v_cndmask_b32_e64 v10, v10, v11, s[40:41]
	v_add_u32_e32 v11, v9, v10
	v_lshrrev_b32_e32 v11, 1, v11
	v_lshl_add_u32 v12, v11, 2, v8
	ds_read_b32 v12, v12
	v_cmp_lt_u32_e32 vcc, v9, v10
	v_add_u32_e32 v13, 1, v11
	s_waitcnt lgkmcnt(0)
	v_sub_f32_e32 v12, v5, v12
	v_cmp_lt_f32_e64 s[40:41], v12, -v7
	s_nop 1
	s_and_b64 s[24:25], vcc, s[40:41]
	s_andn2_b64 s[40:41], vcc, s[40:41]
	s_nop 0
	v_cndmask_b32_e64 v9, v9, v13, s[24:25]
	v_cndmask_b32_e64 v10, v10, v11, s[40:41]
	v_add_u32_e32 v11, v9, v10
	v_lshrrev_b32_e32 v11, 1, v11
	v_lshl_add_u32 v12, v11, 2, v8
	ds_read_b32 v12, v12
	v_cmp_lt_u32_e32 vcc, v9, v10
	v_add_u32_e32 v13, 1, v11
	s_waitcnt lgkmcnt(0)
	v_sub_f32_e32 v12, v5, v12
	v_cmp_lt_f32_e64 s[40:41], v12, -v7
	s_nop 1
	s_and_b64 s[24:25], vcc, s[40:41]
	s_andn2_b64 s[40:41], vcc, s[40:41]
	s_nop 0
	v_cndmask_b32_e64 v9, v9, v13, s[24:25]
	v_cndmask_b32_e64 v10, v10, v11, s[40:41]
	v_add_u32_e32 v11, v9, v10
	v_lshrrev_b32_e32 v11, 1, v11
	v_lshl_add_u32 v12, v11, 2, v8
	ds_read_b32 v12, v12
	v_cmp_lt_u32_e32 vcc, v9, v10
	v_add_u32_e32 v13, 1, v11
	s_waitcnt lgkmcnt(0)
	v_sub_f32_e32 v12, v5, v12
	v_cmp_lt_f32_e64 s[40:41], v12, -v7
	s_nop 1
	s_and_b64 s[24:25], vcc, s[40:41]
	s_andn2_b64 s[40:41], vcc, s[40:41]
	s_nop 0
	v_cndmask_b32_e64 v9, v9, v13, s[24:25]
	v_cndmask_b32_e64 v10, v10, v11, s[40:41]
	v_add_u32_e32 v11, v9, v10
	v_lshrrev_b32_e32 v11, 1, v11
	v_lshl_add_u32 v12, v11, 2, v8
	ds_read_b32 v12, v12
	v_cmp_lt_u32_e32 vcc, v9, v10
	v_add_u32_e32 v13, 1, v11
	s_waitcnt lgkmcnt(0)
	v_sub_f32_e32 v12, v5, v12
	v_cmp_lt_f32_e64 s[40:41], v12, -v7
	s_nop 1
	s_and_b64 s[24:25], vcc, s[40:41]
	s_andn2_b64 s[40:41], vcc, s[40:41]
	s_nop 0
	v_cndmask_b32_e64 v9, v9, v13, s[24:25]
	v_cndmask_b32_e64 v10, v10, v11, s[40:41]
	v_add_u32_e32 v11, v9, v10
	v_lshrrev_b32_e32 v11, 1, v11
	v_lshl_add_u32 v12, v11, 2, v8
	ds_read_b32 v12, v12
	v_cmp_lt_u32_e32 vcc, v9, v10
	v_add_u32_e32 v13, 1, v11
	s_waitcnt lgkmcnt(0)
	v_sub_f32_e32 v12, v5, v12
	v_cmp_lt_f32_e64 s[40:41], v12, -v7
	s_nop 1
	s_and_b64 s[24:25], vcc, s[40:41]
	s_andn2_b64 s[40:41], vcc, s[40:41]
	s_nop 0
	v_cndmask_b32_e64 v9, v9, v13, s[24:25]
	v_cndmask_b32_e64 v10, v10, v11, s[40:41]
	v_mov_b32_e32 v6, v9

.LBB0_344:
	s_or_b64 exec, exec, s[10:11]
	v_add_u32_e32 v168, s49, v209
	v_lshlrev_b32_e32 v168, s47, v168
	s_lshl_b32 s14, s26, 6
	v_add_u32_e32 v128, s48, v168
	v_mov_b64_e32 v[166:167], s[0:1]
	v_mad_i64_i32 v[166:167], s[10:11], v128, s35, v[166:167]
	s_lshl_b32 s14, s14, 1
	v_lshl_add_u64 v[166:167], v[166:167], 0, s[14:15]
	v_lshlrev_b32_e32 v168, 1, v176
	v_mov_b32_e32 v169, 0
	v_lshl_add_u64 v[166:167], v[166:167], 0, v[168:169]
	global_load_dwordx4 v[112:115], v[166:167], off
	global_load_dwordx4 v[116:119], v[166:167], off offset:32
	global_load_dwordx4 v[120:123], v[166:167], off offset:64
	global_load_dwordx4 v[124:127], v[166:167], off offset:96
	s_waitcnt vmcnt(5)
	v_add_u32_e32 v0, v206, v207
	s_waitcnt vmcnt(4)
	ds_write_b128 v0, v[6:9]
	v_add_u32_e32 v6, v206, v208
	ds_write_b128 v6, v[10:13] offset:55296
	ds_write_b128 v0, v[14:17] offset:9216
	ds_write_b128 v196, v[18:21] offset:55296
	ds_write_b128 v0, v[22:25] offset:18432
	ds_write_b128 v202, v[2:5] offset:55296
	ds_write_b128 v0, v[34:37] offset:27648
	ds_write_b128 v203, v[30:33] offset:55296
	ds_write_b128 v0, v[38:41] offset:36864
	ds_write_b128 v204, v[26:29] offset:55296
	ds_write_b128 v0, v[46:49] offset:46080
	ds_write_b128 v238, v[42:45] offset:55296
	v_readlane_b32 s10, v254, 41
	s_cmp_eq_u32 s43, 0
	s_nop 0
	v_mov_b32_e32 v0, s10
	ds_read_b32 v0, v0
	s_waitcnt lgkmcnt(0)
	s_barrier
	v_xor_b32_e32 v16, 0x80000000, v0
	s_cbranch_scc1 .LBB0_347
	ds_read_b64_tr_b16 v[2:3], v240 offset:55296
	ds_read_b64_tr_b16 v[4:5], v240 offset:56832
	ds_read_b64_tr_b16 v[6:7], v240 offset:58368
	ds_read_b64_tr_b16 v[8:9], v240 offset:59904
	ds_read_b64_tr_b16 v[10:11], v240 offset:55360
	ds_read_b64_tr_b16 v[12:13], v240 offset:56896
	ds_read_b64_tr_b16 v[64:65], v240 offset:58432
	ds_read_b64_tr_b16 v[66:67], v240 offset:59968
	ds_read_b128 v[48:51], v239 offset:96
	ds_read_b128 v[52:55], v239 offset:64
	ds_read_b128 v[56:59], v239
	ds_read_b128 v[60:63], v239 offset:32
	v_mov_b32_e32 v17, v16
	v_mov_b32_e32 v18, v16
	v_mov_b32_e32 v19, v16
	v_mov_b32_e32 v20, v16
	v_mov_b32_e32 v21, v16
	v_mov_b32_e32 v22, v16
	v_mov_b32_e32 v23, v16
	v_mov_b32_e32 v24, v16
	v_mov_b32_e32 v25, v16
	v_mov_b32_e32 v26, v16
	v_mov_b32_e32 v27, v16
	v_mov_b32_e32 v28, v16
	v_mov_b32_e32 v29, v16
	v_mov_b32_e32 v30, v16
	v_mov_b32_e32 v31, v16
	s_waitcnt lgkmcnt(0)
	v_readlane_b32 s10, v254, 50
	v_readlane_b32 s11, v254, 51
	s_waitcnt vmcnt(3)
	v_mfma_f32_32x32x16_bf16 v[32:47], v[56:59], v[112:115], v[16:31]
	s_waitcnt vmcnt(2)
	v_mfma_f32_32x32x16_bf16 v[32:47], v[60:63], v[116:119], v[32:47]
	s_waitcnt vmcnt(1)
	v_mfma_f32_32x32x16_bf16 v[32:47], v[52:55], v[120:123], v[32:47]
	s_waitcnt vmcnt(0)
	v_mfma_f32_32x32x16_bf16 v[32:47], v[48:51], v[124:127], v[32:47]
	s_nop 11
	v_cndmask_b32_e64 v0, v32, v201, s[72:73]
	v_cndmask_b32_e64 v32, v35, v201, s[10:11]
	v_readlane_b32 s10, v254, 52
	v_readlane_b32 s11, v254, 53
	v_cndmask_b32_e64 v14, v33, v201, s[74:75]
	v_cndmask_b32_e64 v15, v34, v201, s[78:79]
	v_cndmask_b32_e64 v33, v36, v201, s[10:11]
	v_readlane_b32 s10, v254, 54
	v_readlane_b32 s11, v254, 55
	v_exp_f32_e32 v0, v0
	v_exp_f32_e32 v14, v14
	v_cndmask_b32_e64 v34, v37, v201, s[10:11]
	v_readlane_b32 s10, v254, 56
	v_readlane_b32 s11, v254, 57
	v_exp_f32_e32 v15, v15
	v_exp_f32_e32 v34, v34
	v_cndmask_b32_e64 v35, v38, v201, s[10:11]
	v_readlane_b32 s10, v254, 58
	v_readlane_b32 s11, v254, 59
	v_exp_f32_e32 v35, v35
	s_nop 0
	v_cndmask_b32_e64 v36, v39, v201, s[10:11]
	v_readlane_b32 s10, v254, 60
	v_readlane_b32 s11, v254, 61
	v_exp_f32_e32 v36, v36
	s_nop 0
	v_cndmask_b32_e64 v37, v40, v201, s[10:11]
	v_readlane_b32 s10, v254, 62
	v_readlane_b32 s11, v254, 63
	v_exp_f32_e32 v37, v37
	s_nop 0
	v_cndmask_b32_e64 v38, v41, v201, s[10:11]
	v_readlane_b32 s10, v255, 0
	v_readlane_b32 s11, v255, 1
	v_exp_f32_e32 v38, v38
	s_nop 0
	v_cndmask_b32_e64 v39, v42, v201, s[10:11]
	v_readlane_b32 s10, v255, 2
	v_readlane_b32 s11, v255, 3
	v_exp_f32_e32 v39, v39
	s_nop 0
	v_cndmask_b32_e64 v40, v43, v201, s[10:11]
	v_readlane_b32 s10, v255, 4
	v_readlane_b32 s11, v255, 5
	v_exp_f32_e32 v40, v40
	s_nop 0
	v_cndmask_b32_e64 v41, v44, v201, s[10:11]
	v_readlane_b32 s10, v255, 6
	v_readlane_b32 s11, v255, 7
	v_exp_f32_e32 v41, v41
	s_nop 0
	v_cndmask_b32_e64 v42, v45, v201, s[10:11]
	v_readlane_b32 s10, v255, 8
	v_readlane_b32 s11, v255, 9
	v_add_f32_e32 v45, 0, v0
	v_add_f32_e32 v45, v14, v45
	v_cndmask_b32_e64 v43, v46, v201, s[10:11]
	v_exp_f32_e32 v46, v32
	v_add_f32_e32 v45, v15, v45
	v_readlane_b32 s10, v255, 10
	v_readlane_b32 s11, v255, 11
	v_add_f32_e32 v32, v46, v45
	v_exp_f32_e32 v45, v33
	v_exp_f32_e32 v42, v42
	v_cndmask_b32_e64 v44, v47, v201, s[10:11]
	v_exp_f32_e32 v43, v43
	v_add_f32_e32 v32, v45, v32
	v_add_f32_e32 v32, v34, v32
	v_add_f32_e32 v32, v35, v32
	v_add_f32_e32 v32, v36, v32
	v_add_f32_e32 v32, v37, v32
	v_add_f32_e32 v32, v38, v32
	v_add_f32_e32 v32, v39, v32
	v_add_f32_e32 v32, v40, v32
	v_exp_f32_e32 v44, v44
	v_add_f32_e32 v32, v41, v32
	v_add_f32_e32 v32, v42, v32
	v_add_f32_e32 v32, v43, v32
	v_add_f32_e32 v129, v44, v32
	v_cvt_pk_bf16_f32 v32, v0, v14
	v_cvt_pk_bf16_f32 v33, v15, v46
	v_cvt_pk_bf16_f32 v34, v45, v34
	v_cvt_pk_bf16_f32 v35, v35, v36
	v_cvt_pk_bf16_f32 v68, v37, v38
	v_cvt_pk_bf16_f32 v69, v39, v40
	v_cvt_pk_bf16_f32 v70, v41, v42
	v_cvt_pk_bf16_f32 v71, v43, v44
	s_nop 0
	v_mfma_f32_32x32x16_bf16 v[48:63], v[2:5], v[32:35], 0
	v_mfma_f32_32x32x16_bf16 v[32:47], v[10:13], v[32:35], 0
	v_mfma_f32_32x32x16_bf16 v[48:63], v[6:9], v[68:71], v[48:63]
	v_mfma_f32_32x32x16_bf16 v[32:47], v[64:67], v[68:71], v[32:47]
	ds_read_b128 v[2:5], v241 offset:96
	ds_read_b128 v[6:9], v241 offset:64
	ds_read_b128 v[10:13], v241
	ds_read_b128 v[130:133], v241 offset:32
	ds_read_b128 v[134:137], v241 offset:4704
	ds_read_b128 v[138:141], v241 offset:4672
	ds_read_b128 v[142:145], v241 offset:4640
	ds_read_b128 v[64:67], v241 offset:4608
	ds_read_b128 v[146:149], v241 offset:9312
	ds_read_b128 v[150:153], v241 offset:9280
	ds_read_b128 v[154:157], v241 offset:9248
	ds_read_b128 v[158:161], v241 offset:9216
	s_waitcnt lgkmcnt(8)
	s_waitcnt lgkmcnt(4)
	s_waitcnt lgkmcnt(0)
	v_mfma_f32_32x32x16_bf16 v[96:111], v[10:13], v[112:115], v[16:31]
	v_mfma_f32_32x32x16_bf16 v[80:95], v[64:67], v[112:115], v[16:31]
	v_mfma_f32_32x32x16_bf16 v[96:111], v[130:133], v[116:119], v[96:111]
	v_mfma_f32_32x32x16_bf16 v[64:79], v[158:161], v[112:115], v[16:31]
	v_mfma_f32_32x32x16_bf16 v[80:95], v[142:145], v[116:119], v[80:95]
	v_mfma_f32_32x32x16_bf16 v[96:111], v[6:9], v[120:123], v[96:111]
	v_mfma_f32_32x32x16_bf16 v[64:79], v[154:157], v[116:119], v[64:79]
	v_mfma_f32_32x32x16_bf16 v[80:95], v[138:141], v[120:123], v[80:95]
	v_mfma_f32_32x32x16_bf16 v[96:111], v[2:5], v[124:127], v[96:111]
	ds_read_b64_tr_b16 v[2:3], v242 offset:55296
	ds_read_b64_tr_b16 v[4:5], v242 offset:56832
	ds_read_b64_tr_b16 v[6:7], v243 offset:55296
	ds_read_b64_tr_b16 v[8:9], v243 offset:56832
	ds_read_b64_tr_b16 v[10:11], v242 offset:55360
	ds_read_b64_tr_b16 v[12:13], v242 offset:56896
	ds_read_b64_tr_b16 v[130:131], v243 offset:55360
	ds_read_b64_tr_b16 v[132:133], v243 offset:56896
	v_mfma_f32_32x32x16_bf16 v[64:79], v[150:153], v[120:123], v[64:79]
	v_mfma_f32_32x32x16_bf16 v[80:95], v[134:137], v[124:127], v[80:95]
	v_mfma_f32_32x32x16_bf16 v[64:79], v[146:149], v[124:127], v[64:79]
	s_nop 0
	v_exp_f32_e32 v0, v96
	v_exp_f32_e32 v134, v97
	v_exp_f32_e32 v136, v98
	v_exp_f32_e32 v138, v99
	v_exp_f32_e32 v140, v100
	v_exp_f32_e32 v142, v101
	v_exp_f32_e32 v144, v102
	v_exp_f32_e32 v146, v103
	v_exp_f32_e32 v148, v104
	v_exp_f32_e32 v150, v105
	v_exp_f32_e32 v152, v106
	v_exp_f32_e32 v154, v107
	v_exp_f32_e32 v156, v108
	v_exp_f32_e32 v158, v109
	v_exp_f32_e32 v160, v110
	v_exp_f32_e32 v162, v111
	v_cvt_pk_bf16_f32 v96, v0, v134
	v_cvt_pk_bf16_f32 v97, v136, v138
	v_cvt_pk_bf16_f32 v98, v140, v142
	v_cvt_pk_bf16_f32 v99, v144, v146
	v_cvt_pk_bf16_f32 v100, v148, v150
	v_cvt_pk_bf16_f32 v101, v152, v154
	v_cvt_pk_bf16_f32 v102, v156, v158
	v_cvt_pk_bf16_f32 v103, v160, v162
	s_waitcnt lgkmcnt(0)
	s_nop 0
	v_mfma_f32_32x32x16_bf16 v[48:63], v[2:5], v[96:99], v[48:63]
	v_mfma_f32_32x32x16_bf16 v[32:47], v[10:13], v[96:99], v[32:47]
	v_mfma_f32_32x32x16_bf16 v[48:63], v[6:9], v[100:103], v[48:63]
	ds_read_b64_tr_b16 v[2:3], v244 offset:55296
	ds_read_b64_tr_b16 v[4:5], v244 offset:56832
	ds_read_b64_tr_b16 v[8:9], v244 offset:56896
	ds_read_b64_tr_b16 v[6:7], v244 offset:55360
	ds_read_b64_tr_b16 v[10:11], v245 offset:55296
	ds_read_b64_tr_b16 v[12:13], v245 offset:56832
	ds_read_b64_tr_b16 v[98:99], v245 offset:56896
	ds_read_b64_tr_b16 v[96:97], v245 offset:55360
	v_mfma_f32_32x32x16_bf16 v[32:47], v[130:133], v[100:103], v[32:47]
	v_exp_f32_e32 v135, v80
	v_exp_f32_e32 v137, v81
	v_exp_f32_e32 v139, v82
	v_exp_f32_e32 v141, v83
	v_exp_f32_e32 v143, v84
	v_exp_f32_e32 v145, v85
	v_exp_f32_e32 v147, v86
	v_exp_f32_e32 v149, v87
	v_exp_f32_e32 v151, v88
	v_exp_f32_e32 v153, v89
	v_exp_f32_e32 v155, v90
	v_exp_f32_e32 v157, v91
	v_exp_f32_e32 v159, v92
	v_exp_f32_e32 v161, v93
	v_exp_f32_e32 v163, v94
	v_exp_f32_e32 v131, v95
	v_cvt_pk_bf16_f32 v80, v135, v137
	v_cvt_pk_bf16_f32 v81, v139, v141
	v_cvt_pk_bf16_f32 v82, v143, v145
	v_cvt_pk_bf16_f32 v83, v147, v149
	v_cvt_pk_bf16_f32 v84, v151, v153
	v_cvt_pk_bf16_f32 v85, v155, v157
	v_cvt_pk_bf16_f32 v86, v159, v161
	v_cvt_pk_bf16_f32 v87, v163, v131
	s_waitcnt lgkmcnt(0)
	s_nop 0
	v_mfma_f32_32x32x16_bf16 v[48:63], v[2:5], v[80:83], v[48:63]
	v_mfma_f32_32x32x16_bf16 v[32:47], v[6:9], v[80:83], v[32:47]
	v_mfma_f32_32x32x16_bf16 v[48:63], v[10:13], v[84:87], v[48:63]
	ds_read_b64_tr_b16 v[2:3], v246 offset:55296
	ds_read_b64_tr_b16 v[4:5], v246 offset:56832
	ds_read_b64_tr_b16 v[8:9], v246 offset:56896
	ds_read_b64_tr_b16 v[6:7], v246 offset:55360
	ds_read_b64_tr_b16 v[10:11], v247 offset:55296
	ds_read_b64_tr_b16 v[12:13], v247 offset:56832
	ds_read_b64_tr_b16 v[82:83], v247 offset:56896
	ds_read_b64_tr_b16 v[80:81], v247 offset:55360
	v_mfma_f32_32x32x16_bf16 v[32:47], v[96:99], v[84:87], v[32:47]
	v_exp_f32_e32 v15, v64
	v_exp_f32_e32 v84, v65
	v_exp_f32_e32 v92, v66
	v_exp_f32_e32 v90, v67
	v_exp_f32_e32 v100, v68
	v_exp_f32_e32 v98, v69
	v_exp_f32_e32 v108, v70
	v_exp_f32_e32 v106, v71
	v_exp_f32_e32 v110, v72
	v_exp_f32_e32 v14, v73
	v_exp_f32_e32 v88, v74
	v_exp_f32_e32 v86, v75
	v_exp_f32_e32 v96, v76
	v_exp_f32_e32 v94, v77
	v_exp_f32_e32 v104, v78
	v_exp_f32_e32 v102, v79
	v_cvt_pk_bf16_f32 v64, v15, v84
	v_cvt_pk_bf16_f32 v65, v92, v90
	v_cvt_pk_bf16_f32 v66, v100, v98
	v_cvt_pk_bf16_f32 v67, v108, v106
	v_cvt_pk_bf16_f32 v68, v110, v14
	v_cvt_pk_bf16_f32 v69, v88, v86
	v_cvt_pk_bf16_f32 v70, v96, v94
	v_cvt_pk_bf16_f32 v71, v104, v102
	s_waitcnt lgkmcnt(0)
	v_add_f32_e32 v0, 0, v0
	v_mfma_f32_32x32x16_bf16 v[48:63], v[2:5], v[64:67], v[48:63]
	v_add_f32_e64 v2, v134, v0
	v_add_f32_e64 v3, v135, v1
	v_add_f32_e32 v130, 0, v129
	v_add_f32_e64 v2, v136, v2
	v_add_f32_e64 v3, v137, v3
	v_readlane_b32 s10, v255, 12
	v_pk_add_f32 v[2:3], v[138:139], v[2:3]
	v_readlane_b32 s11, v255, 13
	v_pk_add_f32 v[2:3], v[140:141], v[2:3]
	v_mfma_f32_32x32x16_bf16 v[32:47], v[6:9], v[64:67], v[32:47]
	v_add_f32_e64 v2, v142, v2
	v_add_f32_e64 v3, v143, v3
	v_add_f32_e32 v0, 0, v15
	v_add_f32_e64 v2, v144, v2
	v_add_f32_e64 v3, v145, v3
	v_pk_add_f32 v[2:3], v[146:147], v[2:3]
	s_nop 0
	v_pk_add_f32 v[2:3], v[148:149], v[2:3]
	v_mfma_f32_32x32x16_bf16 v[48:63], v[10:13], v[68:71], v[48:63]
	v_add_f32_e64 v2, v150, v2
	v_add_f32_e64 v3, v151, v3
	v_add_f32_e64 v2, v152, v2
	v_add_f32_e64 v3, v153, v3
	v_add_f32_e64 v2, v154, v2
	v_add_f32_e64 v3, v155, v3
	v_pk_add_f32 v[2:3], v[156:157], v[2:3]
	v_mfma_f32_32x32x16_bf16 v[32:47], v[80:83], v[68:71], v[32:47]
	v_add_f32_e64 v2, v158, v2
	v_add_f32_e64 v3, v159, v3
	v_mov_b64_e32 v[78:79], v[30:31]
	v_add_f32_e64 v2, v160, v2
	v_add_f32_e64 v3, v161, v3
	v_mov_b64_e32 v[76:77], v[28:29]
	v_pk_add_f32 v[2:3], v[162:163], v[2:3]
	v_mov_b64_e32 v[74:75], v[26:27]
	v_pk_add_f32 v[130:131], v[130:131], v[2:3]
	ds_read_b64_tr_b16 v[80:81], v249 offset:55296
	ds_read_b64_tr_b16 v[82:83], v249 offset:56832
	ds_read_b64_tr_b16 v[10:11], v250 offset:55296
	ds_read_b64_tr_b16 v[12:13], v250 offset:56832
	ds_read_b64_tr_b16 v[6:7], v249 offset:55360
	ds_read_b64_tr_b16 v[8:9], v249 offset:56896
	ds_read_b64_tr_b16 v[2:3], v250 offset:55360
	ds_read_b64_tr_b16 v[4:5], v250 offset:56896
	ds_read_b128 v[132:135], v248 offset:96
	ds_read_b128 v[136:139], v248 offset:64
	ds_read_b128 v[140:143], v248
	ds_read_b128 v[144:147], v248 offset:32
	v_mov_b64_e32 v[72:73], v[24:25]
	v_mov_b64_e32 v[70:71], v[22:23]
	v_mov_b64_e32 v[68:69], v[20:21]
	v_mov_b64_e32 v[66:67], v[18:19]
	v_mov_b64_e32 v[64:65], v[16:17]
	s_waitcnt lgkmcnt(0)
	s_nop 0
	v_mfma_f32_32x32x16_bf16 v[64:79], v[140:143], v[112:115], v[64:79]
	v_mfma_f32_32x32x16_bf16 v[64:79], v[144:147], v[116:119], v[64:79]
	v_mfma_f32_32x32x16_bf16 v[64:79], v[136:139], v[120:123], v[64:79]
	v_mfma_f32_32x32x16_bf16 v[64:79], v[132:135], v[124:127], v[64:79]
	s_nop 11
	v_cndmask_b32_e64 v15, v64, v201, s[10:11]
	v_readlane_b32 s10, v255, 14
	v_readlane_b32 s11, v255, 15
	v_cndmask_b32_e64 v15, v15, v64, s[44:45]
	v_cndmask_b32_e64 v17, v201, v65, s[44:45]
	v_cndmask_b32_e64 v18, v66, v201, s[10:11]
	v_readlane_b32 s10, v255, 16
	v_readlane_b32 s11, v255, 17
	v_exp_f32_e32 v85, v15
	v_exp_f32_e32 v93, v17
	v_cndmask_b32_e64 v19, v67, v201, s[10:11]
	v_readlane_b32 s10, v255, 18
	v_readlane_b32 s11, v255, 19
	v_exp_f32_e32 v91, v18
	v_exp_f32_e32 v101, v19
	v_cndmask_b32_e64 v20, v68, v201, s[10:11]
	v_readlane_b32 s10, v255, 20
	v_readlane_b32 s11, v255, 21
	v_pk_add_f32 v[18:19], v[84:85], v[0:1]
	v_exp_f32_e32 v99, v20
	v_cndmask_b32_e64 v21, v69, v201, s[10:11]
	v_readlane_b32 s10, v255, 22
	v_readlane_b32 s11, v255, 23
	v_pk_add_f32 v[18:19], v[92:93], v[18:19]
	v_exp_f32_e32 v109, v21
	v_cndmask_b32_e64 v22, v70, v201, s[10:11]
	v_cndmask_b32_e64 v23, v71, v201, s[56:57]
	v_pk_add_f32 v[18:19], v[90:91], v[18:19]
	v_exp_f32_e32 v107, v22
	v_cndmask_b32_e64 v24, v72, v201, s[58:59]
	v_pk_add_f32 v[18:19], v[100:101], v[18:19]
	v_exp_f32_e32 v111, v23
	v_cndmask_b32_e64 v25, v73, v201, s[60:61]
	v_exp_f32_e32 v15, v24
	v_pk_add_f32 v[18:19], v[98:99], v[18:19]
	v_cndmask_b32_e64 v26, v74, v201, s[62:63]
	v_exp_f32_e32 v89, v25
	v_pk_add_f32 v[18:19], v[108:109], v[18:19]
	v_cndmask_b32_e64 v27, v75, v201, s[64:65]
	v_exp_f32_e32 v87, v26
	v_pk_add_f32 v[18:19], v[106:107], v[18:19]
	v_cndmask_b32_e64 v28, v76, v201, s[66:67]
	v_exp_f32_e32 v97, v27
	v_pk_add_f32 v[18:19], v[110:111], v[18:19]
	v_cndmask_b32_e64 v29, v77, v201, s[40:41]
	v_exp_f32_e32 v95, v28
	v_pk_add_f32 v[18:19], v[14:15], v[18:19]
	v_cndmask_b32_e64 v30, v78, v201, s[8:9]
	v_cndmask_b32_e64 v31, v79, v201, s[4:5]
	v_exp_f32_e32 v105, v29
	v_pk_add_f32 v[18:19], v[88:89], v[18:19]
	v_exp_f32_e32 v103, v30
	v_exp_f32_e32 v0, v31
	v_pk_add_f32 v[18:19], v[86:87], v[18:19]
	v_pk_add_f32 v[20:21], v[130:131], v[130:131] op_sel:[0,1] op_sel_hi:[1,0]
	v_pk_add_f32 v[18:19], v[96:97], v[18:19]
	v_mov_b32_e32 v21, v0
	v_pk_add_f32 v[18:19], v[94:95], v[18:19]
	s_nop 0
	v_pk_add_f32 v[18:19], v[104:105], v[18:19]
	s_nop 0
	v_pk_add_f32 v[18:19], v[102:103], v[18:19]
	s_nop 0
	v_pk_add_f32 v[18:19], v[20:21], v[18:19]
	s_nop 0
	v_add_f32_e32 v84, v18, v19
	v_cvt_pk_bf16_f32 v18, v85, v93
	v_cvt_pk_bf16_f32 v19, v91, v101
	v_cvt_pk_bf16_f32 v20, v99, v109
	v_cvt_pk_bf16_f32 v21, v107, v111
	v_cvt_pk_bf16_f32 v22, v15, v89
	v_cvt_pk_bf16_f32 v23, v87, v97
	v_cvt_pk_bf16_f32 v24, v95, v105
	v_cvt_pk_bf16_f32 v25, v103, v0
	s_nop 0
	v_mfma_f32_32x32x16_bf16 v[48:63], v[80:83], v[18:21], v[48:63]
	v_mfma_f32_32x32x16_bf16 v[32:47], v[6:9], v[18:21], v[32:47]
	v_mfma_f32_32x32x16_bf16 v[48:63], v[10:13], v[22:25], v[48:63]
	v_mfma_f32_32x32x16_bf16 v[32:47], v[2:5], v[22:25], v[32:47]
	s_cbranch_execz .LBB0_348
	s_branch .LBB0_352
